# code placement: heads of the three hand-written streaming loops (P0 x-row steady body, P0 p group loop, final RMSNorm loop) aligned to 64 B with s_nop fill; on top of v031
# speedup vs baseline: 1.0132x; 1.0132x over previous
; __device__ __forceinline__ unsigned pk2(float lo, float hi) { return f2bf(lo) | (f2bf(hi) << 16); }
; __device__ __forceinline__ void p0_prologue(const Args& a, LAS unsigned char* lds) {
;     ...
;     { const float* x = a.in[0]; bf16* xb = (bf16*)(ws + WS_XB0); float* ss0 = (float*)(ws + WS_SS0);
;       for (int m = gw; m < M; m += NGW) { const f32x4* xr = (const f32x4*)(x + (size_t)m * D) + lane; u32x2* o8 = (u32x2*)(xb + (size_t)(m >> 8) * 8 * 65536 + (size_t)(m & 255) * 256) + lane; float s = 0.f;
; #pragma unroll
;           for (int j = 0; j < 8; ++j) { const f32x4 v = __builtin_nontemporal_load(xr + 64 * j); s += (v[0] * v[0] + v[1] * v[1]) + (v[2] * v[2] + v[3] * v[3]); u32x2 w; w.x = pk2(v[0], v[1]); w.y = pk2(v[2], v[3]); o8[(size_t)j * (65536 / 4)] = w; }
;           s = wave_sum(s); if (lane < 32) ss0[(size_t)m * 32 + lane] = lane == 0 ? s : 0.f; } }
.Lxcv_first:
	s_waitcnt vmcnt(7)
	v_and_b32_sdwa v5, v27, v22 dst_sel:DWORD dst_unused:UNUSED_PAD src0_sel:WORD_1 src1_sel:DWORD
	v_and_b32_sdwa v7, v25, v22 dst_sel:DWORD dst_unused:UNUSED_PAD src0_sel:WORD_1 src1_sel:DWORD
	v_and_b32_sdwa v6, v26, v22 dst_sel:DWORD dst_unused:UNUSED_PAD src0_sel:WORD_1 src1_sel:DWORD
	v_and_b32_sdwa v23, v24, v22 dst_sel:DWORD dst_unused:UNUSED_PAD src0_sel:WORD_1 src1_sel:DWORD
	v_add3_u32 v5, v27, v5, s18
	v_add3_u32 v7, v25, v7, s18
	v_add3_u32 v23, v24, v23, s18
	v_add3_u32 v6, v26, v6, s18
	v_and_b32_e32 v5, 0xffff0000, v5
	v_and_b32_e32 v7, 0xffff0000, v7
	v_or_b32_sdwa v65, v5, v6 dst_sel:DWORD dst_unused:UNUSED_PAD src0_sel:DWORD src1_sel:WORD_1
	v_or_b32_sdwa v64, v7, v23 dst_sel:DWORD dst_unused:UNUSED_PAD src0_sel:DWORD src1_sel:WORD_1
	v_mul_f32_e32 v3, v25, v25
	v_mul_f32_e32 v4, v27, v27
	global_store_dwordx2 v11, v[64:65], s[12:13] nt
	v_fmac_f32_e32 v3, v24, v24
	v_fmac_f32_e32 v4, v26, v26
	v_add_f32_e32 v2, v3, v4
	s_mov_b64 exec, s[20:21]
	global_load_dwordx4 v[24:27], v10, s[14:15] offset:-4096 nt
	s_mov_b64 exec, s[22:23]
	s_waitcnt vmcnt(7)
	v_and_b32_sdwa v5, v31, v22 dst_sel:DWORD dst_unused:UNUSED_PAD src0_sel:WORD_1 src1_sel:DWORD
	v_and_b32_sdwa v7, v29, v22 dst_sel:DWORD dst_unused:UNUSED_PAD src0_sel:WORD_1 src1_sel:DWORD
	v_and_b32_sdwa v6, v30, v22 dst_sel:DWORD dst_unused:UNUSED_PAD src0_sel:WORD_1 src1_sel:DWORD
	v_and_b32_sdwa v23, v28, v22 dst_sel:DWORD dst_unused:UNUSED_PAD src0_sel:WORD_1 src1_sel:DWORD
	v_add3_u32 v5, v31, v5, s18
	v_add3_u32 v7, v29, v7, s18
	v_add3_u32 v23, v28, v23, s18
	v_add3_u32 v6, v30, v6, s18
	v_and_b32_e32 v5, 0xffff0000, v5
	v_and_b32_e32 v7, 0xffff0000, v7
	s_add_u32 s24, s12, 0x20000
	s_addc_u32 s25, s13, 0
	v_or_b32_sdwa v67, v5, v6 dst_sel:DWORD dst_unused:UNUSED_PAD src0_sel:DWORD src1_sel:WORD_1
	v_or_b32_sdwa v66, v7, v23 dst_sel:DWORD dst_unused:UNUSED_PAD src0_sel:DWORD src1_sel:WORD_1
	v_mul_f32_e32 v3, v29, v29
	v_mul_f32_e32 v4, v31, v31
	global_store_dwordx2 v11, v[66:67], s[24:25] nt
	v_fmac_f32_e32 v3, v28, v28
	v_fmac_f32_e32 v4, v30, v30
	v_add_f32_e32 v3, v3, v4
	v_add_f32_e32 v2, v2, v3
	s_mov_b64 exec, s[20:21]
	global_load_dwordx4 v[28:31], v10, s[14:15] offset:-3072 nt
	s_mov_b64 exec, s[22:23]
	s_waitcnt vmcnt(7)
	v_and_b32_sdwa v5, v35, v22 dst_sel:DWORD dst_unused:UNUSED_PAD src0_sel:WORD_1 src1_sel:DWORD
	v_and_b32_sdwa v7, v33, v22 dst_sel:DWORD dst_unused:UNUSED_PAD src0_sel:WORD_1 src1_sel:DWORD
	v_and_b32_sdwa v6, v34, v22 dst_sel:DWORD dst_unused:UNUSED_PAD src0_sel:WORD_1 src1_sel:DWORD
	v_and_b32_sdwa v23, v32, v22 dst_sel:DWORD dst_unused:UNUSED_PAD src0_sel:WORD_1 src1_sel:DWORD
	v_add3_u32 v5, v35, v5, s18
	v_add3_u32 v7, v33, v7, s18
	v_add3_u32 v23, v32, v23, s18
	v_add3_u32 v6, v34, v6, s18
	v_and_b32_e32 v5, 0xffff0000, v5
	v_and_b32_e32 v7, 0xffff0000, v7
	s_add_u32 s24, s12, 0x40000
	s_addc_u32 s25, s13, 0
	v_or_b32_sdwa v69, v5, v6 dst_sel:DWORD dst_unused:UNUSED_PAD src0_sel:DWORD src1_sel:WORD_1
	v_or_b32_sdwa v68, v7, v23 dst_sel:DWORD dst_unused:UNUSED_PAD src0_sel:DWORD src1_sel:WORD_1
	v_mul_f32_e32 v3, v33, v33
	v_mul_f32_e32 v4, v35, v35
	global_store_dwordx2 v11, v[68:69], s[24:25] nt
	v_fmac_f32_e32 v3, v32, v32
	v_fmac_f32_e32 v4, v34, v34
	v_add_f32_e32 v3, v3, v4
	v_add_f32_e32 v2, v2, v3
	s_mov_b64 exec, s[20:21]
	global_load_dwordx4 v[32:35], v10, s[14:15] offset:-2048 nt
	s_mov_b64 exec, s[22:23]
	s_waitcnt vmcnt(7)
	v_and_b32_sdwa v5, v39, v22 dst_sel:DWORD dst_unused:UNUSED_PAD src0_sel:WORD_1 src1_sel:DWORD
	v_and_b32_sdwa v7, v37, v22 dst_sel:DWORD dst_unused:UNUSED_PAD src0_sel:WORD_1 src1_sel:DWORD
	v_and_b32_sdwa v6, v38, v22 dst_sel:DWORD dst_unused:UNUSED_PAD src0_sel:WORD_1 src1_sel:DWORD
	v_and_b32_sdwa v23, v36, v22 dst_sel:DWORD dst_unused:UNUSED_PAD src0_sel:WORD_1 src1_sel:DWORD
	v_add3_u32 v5, v39, v5, s18
	v_add3_u32 v7, v37, v7, s18
	v_add3_u32 v23, v36, v23, s18
	v_add3_u32 v6, v38, v6, s18
	v_and_b32_e32 v5, 0xffff0000, v5
	v_and_b32_e32 v7, 0xffff0000, v7
	s_add_u32 s24, s12, 0x60000
	s_addc_u32 s25, s13, 0
	v_or_b32_sdwa v71, v5, v6 dst_sel:DWORD dst_unused:UNUSED_PAD src0_sel:DWORD src1_sel:WORD_1
	v_or_b32_sdwa v70, v7, v23 dst_sel:DWORD dst_unused:UNUSED_PAD src0_sel:DWORD src1_sel:WORD_1
	v_mul_f32_e32 v3, v37, v37
	v_mul_f32_e32 v4, v39, v39
	global_store_dwordx2 v11, v[70:71], s[24:25] nt
	v_fmac_f32_e32 v3, v36, v36
	v_fmac_f32_e32 v4, v38, v38
	v_add_f32_e32 v3, v3, v4
	v_add_f32_e32 v2, v2, v3
	s_mov_b64 exec, s[20:21]
	global_load_dwordx4 v[36:39], v10, s[14:15] offset:-1024 nt
	s_mov_b64 exec, s[22:23]
	s_waitcnt vmcnt(7)
; __device__ __forceinline__ unsigned pk2(float lo, float hi) { return f2bf(lo) | (f2bf(hi) << 16); }
; __device__ __forceinline__ void p0_prologue(const Args& a, LAS unsigned char* lds) {
;     ...
;     { const float* x = a.in[0]; bf16* xb = (bf16*)(ws + WS_XB0); float* ss0 = (float*)(ws + WS_SS0);
;       for (int m = gw; m < M; m += NGW) { const f32x4* xr = (const f32x4*)(x + (size_t)m * D) + lane; u32x2* o8 = (u32x2*)(xb + (size_t)(m >> 8) * 8 * 65536 + (size_t)(m & 255) * 256) + lane; float s = 0.f;
; #pragma unroll
;           for (int j = 0; j < 8; ++j) { const f32x4 v = __builtin_nontemporal_load(xr + 64 * j); s += (v[0] * v[0] + v[1] * v[1]) + (v[2] * v[2] + v[3] * v[3]); u32x2 w; w.x = pk2(v[0], v[1]); w.y = pk2(v[2], v[3]); o8[(size_t)j * (65536 / 4)] = w; }
;           s = wave_sum(s); if (lane < 32) ss0[(size_t)m * 32 + lane] = lane == 0 ? s : 0.f; } }
	v_and_b32_sdwa v5, v43, v22 dst_sel:DWORD dst_unused:UNUSED_PAD src0_sel:WORD_1 src1_sel:DWORD
	v_and_b32_sdwa v7, v41, v22 dst_sel:DWORD dst_unused:UNUSED_PAD src0_sel:WORD_1 src1_sel:DWORD
	v_and_b32_sdwa v6, v42, v22 dst_sel:DWORD dst_unused:UNUSED_PAD src0_sel:WORD_1 src1_sel:DWORD
	v_and_b32_sdwa v23, v40, v22 dst_sel:DWORD dst_unused:UNUSED_PAD src0_sel:WORD_1 src1_sel:DWORD
	v_add3_u32 v5, v43, v5, s18
	v_add3_u32 v7, v41, v7, s18
	v_add3_u32 v23, v40, v23, s18
	v_add3_u32 v6, v42, v6, s18
	v_and_b32_e32 v5, 0xffff0000, v5
	v_and_b32_e32 v7, 0xffff0000, v7
	s_add_u32 s24, s12, 0x80000
	s_addc_u32 s25, s13, 0
	v_or_b32_sdwa v73, v5, v6 dst_sel:DWORD dst_unused:UNUSED_PAD src0_sel:DWORD src1_sel:WORD_1
	v_or_b32_sdwa v72, v7, v23 dst_sel:DWORD dst_unused:UNUSED_PAD src0_sel:DWORD src1_sel:WORD_1
	v_mul_f32_e32 v3, v41, v41
	v_mul_f32_e32 v4, v43, v43
	global_store_dwordx2 v11, v[72:73], s[24:25] nt
	v_fmac_f32_e32 v3, v40, v40
	v_fmac_f32_e32 v4, v42, v42
	v_add_f32_e32 v3, v3, v4
	v_add_f32_e32 v2, v2, v3
	s_mov_b64 exec, s[20:21]
	global_load_dwordx4 v[40:43], v10, s[14:15] offset:0 nt
	s_mov_b64 exec, s[22:23]
	s_waitcnt vmcnt(7)
	v_and_b32_sdwa v5, v47, v22 dst_sel:DWORD dst_unused:UNUSED_PAD src0_sel:WORD_1 src1_sel:DWORD
	v_and_b32_sdwa v7, v45, v22 dst_sel:DWORD dst_unused:UNUSED_PAD src0_sel:WORD_1 src1_sel:DWORD
	v_and_b32_sdwa v6, v46, v22 dst_sel:DWORD dst_unused:UNUSED_PAD src0_sel:WORD_1 src1_sel:DWORD
	v_and_b32_sdwa v23, v44, v22 dst_sel:DWORD dst_unused:UNUSED_PAD src0_sel:WORD_1 src1_sel:DWORD
	v_add3_u32 v5, v47, v5, s18
	v_add3_u32 v7, v45, v7, s18
	v_add3_u32 v23, v44, v23, s18
	v_add3_u32 v6, v46, v6, s18
	v_and_b32_e32 v5, 0xffff0000, v5
	v_and_b32_e32 v7, 0xffff0000, v7
	s_add_u32 s24, s12, 0xa0000
	s_addc_u32 s25, s13, 0
	v_or_b32_sdwa v75, v5, v6 dst_sel:DWORD dst_unused:UNUSED_PAD src0_sel:DWORD src1_sel:WORD_1
	v_or_b32_sdwa v74, v7, v23 dst_sel:DWORD dst_unused:UNUSED_PAD src0_sel:DWORD src1_sel:WORD_1
	v_mul_f32_e32 v3, v45, v45
	v_mul_f32_e32 v4, v47, v47
	global_store_dwordx2 v11, v[74:75], s[24:25] nt
	v_fmac_f32_e32 v3, v44, v44
	v_fmac_f32_e32 v4, v46, v46
	v_add_f32_e32 v3, v3, v4
	v_add_f32_e32 v2, v2, v3
	s_mov_b64 exec, s[20:21]
	global_load_dwordx4 v[44:47], v10, s[14:15] offset:1024 nt
	s_mov_b64 exec, s[22:23]
	s_waitcnt vmcnt(7)
	v_and_b32_sdwa v5, v51, v22 dst_sel:DWORD dst_unused:UNUSED_PAD src0_sel:WORD_1 src1_sel:DWORD
	v_and_b32_sdwa v7, v49, v22 dst_sel:DWORD dst_unused:UNUSED_PAD src0_sel:WORD_1 src1_sel:DWORD
	v_and_b32_sdwa v6, v50, v22 dst_sel:DWORD dst_unused:UNUSED_PAD src0_sel:WORD_1 src1_sel:DWORD
	v_and_b32_sdwa v23, v48, v22 dst_sel:DWORD dst_unused:UNUSED_PAD src0_sel:WORD_1 src1_sel:DWORD
	v_add3_u32 v5, v51, v5, s18
	v_add3_u32 v7, v49, v7, s18
	v_add3_u32 v23, v48, v23, s18
	v_add3_u32 v6, v50, v6, s18
	v_and_b32_e32 v5, 0xffff0000, v5
	v_and_b32_e32 v7, 0xffff0000, v7
	s_add_u32 s24, s12, 0xc0000
	s_addc_u32 s25, s13, 0
	v_or_b32_sdwa v77, v5, v6 dst_sel:DWORD dst_unused:UNUSED_PAD src0_sel:DWORD src1_sel:WORD_1
	v_or_b32_sdwa v76, v7, v23 dst_sel:DWORD dst_unused:UNUSED_PAD src0_sel:DWORD src1_sel:WORD_1
	v_mul_f32_e32 v3, v49, v49
	v_mul_f32_e32 v4, v51, v51
	global_store_dwordx2 v11, v[76:77], s[24:25] nt
	v_fmac_f32_e32 v3, v48, v48
	v_fmac_f32_e32 v4, v50, v50
	v_add_f32_e32 v3, v3, v4
	v_add_f32_e32 v2, v2, v3
	s_mov_b64 exec, s[20:21]
	global_load_dwordx4 v[48:51], v10, s[14:15] offset:2048 nt
	s_mov_b64 exec, s[22:23]
	s_waitcnt vmcnt(7)
	v_and_b32_sdwa v5, v55, v22 dst_sel:DWORD dst_unused:UNUSED_PAD src0_sel:WORD_1 src1_sel:DWORD
	v_and_b32_sdwa v7, v53, v22 dst_sel:DWORD dst_unused:UNUSED_PAD src0_sel:WORD_1 src1_sel:DWORD
	v_and_b32_sdwa v6, v54, v22 dst_sel:DWORD dst_unused:UNUSED_PAD src0_sel:WORD_1 src1_sel:DWORD
	v_and_b32_sdwa v23, v52, v22 dst_sel:DWORD dst_unused:UNUSED_PAD src0_sel:WORD_1 src1_sel:DWORD
	v_add3_u32 v5, v55, v5, s18
	v_add3_u32 v7, v53, v7, s18
	v_add3_u32 v23, v52, v23, s18
	v_add3_u32 v6, v54, v6, s18
	v_and_b32_e32 v5, 0xffff0000, v5
	v_and_b32_e32 v7, 0xffff0000, v7
	s_add_u32 s24, s12, 0xe0000
	s_addc_u32 s25, s13, 0
	v_or_b32_sdwa v79, v5, v6 dst_sel:DWORD dst_unused:UNUSED_PAD src0_sel:DWORD src1_sel:WORD_1
	v_or_b32_sdwa v78, v7, v23 dst_sel:DWORD dst_unused:UNUSED_PAD src0_sel:DWORD src1_sel:WORD_1
	v_mul_f32_e32 v3, v53, v53
	v_mul_f32_e32 v4, v55, v55
	global_store_dwordx2 v11, v[78:79], s[24:25] nt
	v_fmac_f32_e32 v3, v52, v52
	v_fmac_f32_e32 v4, v54, v54
	v_add_f32_e32 v3, v3, v4
	v_add_f32_e32 v2, v2, v3
	s_mov_b64 exec, s[20:21]
	global_load_dwordx4 v[52:55], v10, s[14:15] offset:3072 nt
	s_mov_b64 exec, s[22:23]
	s_branch .Lxcv_tail
	.p2alignl 6, 3212836864

; __device__ __forceinline__ unsigned pk2(float lo, float hi) { return f2bf(lo) | (f2bf(hi) << 16); }
; __device__ __forceinline__ void p0_prologue(const Args& a, LAS unsigned char* lds) {
;     ...
;     { const float* p = a.in[1]; bf16* pb = (bf16*)(ws + WS_PB); const size_t n8 = (size_t)2 * M * PLE / 8;
;       for (size_t i = (size_t)blockIdx.x * 512 + tid; i < n8; i += (size_t)G * 512) { const f32x4 v0 = *(const f32x4*)(p + i * 8), v1 = *(const f32x4*)(p + i * 8 + 4);
;           u32x4 w; w.x = pk2(v0[0], v0[1]); w.y = pk2(v0[2], v0[3]); w.z = pk2(v1[0], v1[1]); w.w = pk2(v1[2], v1[3]); *(u32x4*)(pb + i * 8) = w; } }
.LBB0_324:
	s_or_b64 exec, exec, s[8:9]
	s_mov_b32 s3, 0
	s_lshl_b64 s[0:1], s[2:3], 9
	v_mov_b32_e32 v201, 0
	s_waitcnt lgkmcnt(0)
	v_lshl_add_u64 v[2:3], s[0:1], 0, v[200:201]
	s_mov_b64 s[0:1], 0x100000
	v_cmp_gt_u64_e32 vcc, s[0:1], v[2:3]
	s_and_saveexec_b64 s[0:1], vcc
	s_cbranch_execz .LBB0_327
	s_load_dwordx2 s[6:7], s[92:93], 0x8
	v_readlane_b32 s4, v254, 7
	v_readlane_b32 s5, v254, 8
	s_mov_b32 s10, s4
	s_ashr_i32 s11, s4, 31
	s_lshl_b64 s[4:5], s[10:11], 9
	s_lshl_b64 s[8:9], s[2:3], 14
	s_waitcnt lgkmcnt(0)
	s_add_u32 s6, s6, s8
	v_lshlrev_b32_e32 v4, 5, v200
	v_mov_b32_e32 v5, v201
	s_addc_u32 s7, s7, s9
	v_lshl_add_u64 v[4:5], s[6:7], 0, v[4:5]
	s_lshl_b64 s[6:7], s[10:11], 14
	s_lshl_b64 s[8:9], s[2:3], 13
	s_add_u32 s8, s74, s8
	s_waitcnt vmcnt(23)
	v_lshlrev_b32_e32 v6, 4, v200
	v_mov_b32_e32 v7, v201
	s_addc_u32 s9, s75, s9
	v_lshl_add_u64 v[6:7], s[8:9], 0, v[6:7]
	s_mov_b64 s[8:9], 0x1000000
	v_lshl_add_u64 v[6:7], v[6:7], 0, s[8:9]
	s_mov_b32 s8, s10
	v_writelane_b32 v254, s8, 7
	v_lshl_add_u64 v[4:5], v[4:5], 0, 16
	s_movk_i32 s3, 0x7fff
	v_writelane_b32 v254, s9, 8
	s_lshl_b64 s[8:9], s[10:11], 13
	s_mov_b64 s[10:11], 0
	s_mov_b32 s14, 0xffff0000
	s_mov_b64 s[12:13], 0xfffff
	v_readlane_b32 s98, v254, 7
	s_nop 1
	s_mul_i32 s100, s98, 3
	s_add_u32 s100, s100, s2
	s_lshl_b32 s101, s98, 2
	s_lshl_b64 s[98:99], s[4:5], 2
	.p2alignl 6, 3212836864

; __device__ __forceinline__ void final_phase(float* x, const float* ssq, const float* gn, bool team) {
;     const int tid = threadIdx.x, lane = tid & 63, wave = tid >> 6; const int gw = blockIdx.x * 8 + wave, NGW = gridDim.x * 8;
;     const int mbeg = team ? my_pm() * 256 + (int)(blockIdx.x >> 6) * 64 + wave : gw, mend = team ? my_pm() * 256 + (int)(blockIdx.x >> 6) * 64 + 64 : M, mstep = team ? 8 : NGW;
;     for (int m = mbeg; m < mend; m += mstep) { float s = ssq[(size_t)m * 32 + (lane & 31)];
; #pragma unroll
;         for (int o = 1; o < 32; o <<= 1) s += __shfl_xor(s, o);
;         const float rs = __builtin_amdgcn_rsqf(s * (1.0f / D) + 1e-6f); f32x4* xr = (f32x4*)(x + (size_t)m * D) + lane; const f32x4* gr = (const f32x4*)gn + lane;
.LBB0_2362:
	v_add_u32_e32 v1, v3, v4
	v_add_u32_e32 v1, 64, v1
	v_mov_b32_e32 v3, 0x4000
	s_waitcnt vmcnt(19)
	v_cndmask_b32_e64 v22, v3, v1, s[88:89]
	v_cmp_lt_i32_e32 vcc, v0, v22
	s_and_saveexec_b64 s[0:1], vcc
	s_cbranch_execz .LBB0_2365
	v_mbcnt_lo_u32_b32 v3, -1, 0
	v_mbcnt_hi_u32_b32 v3, -1, v3
	v_and_b32_e32 v1, 63, v200
	v_and_b32_e32 v4, 64, v3
	v_add_u32_e32 v6, 64, v4
	v_lshlrev_b32_e32 v14, 4, v1
	v_xor_b32_e32 v1, 1, v3
	v_cmp_lt_i32_e32 vcc, v1, v6
	s_load_dwordx4 s[4:7], s[92:93], 0xe8
	v_mov_b32_e32 v15, 0
	v_cndmask_b32_e32 v1, v3, v1, vcc
	v_lshlrev_b32_e32 v23, 2, v1
	v_xor_b32_e32 v1, 2, v3
	v_cmp_lt_i32_e32 vcc, v1, v6
	v_and_b32_e32 v20, 31, v200
	s_waitcnt lgkmcnt(0)
	v_lshl_add_u64 v[4:5], s[4:5], 0, v[14:15]
	v_cndmask_b32_e32 v1, v3, v1, vcc
	v_lshlrev_b32_e32 v24, 2, v1
	v_xor_b32_e32 v1, 4, v3
	v_cmp_lt_i32_e32 vcc, v1, v6
	s_mov_b64 s[2:3], 0x1400
	s_mov_b64 s[0:1], 0x1000
	v_cndmask_b32_e32 v1, v3, v1, vcc
	v_lshlrev_b32_e32 v25, 2, v1
	v_xor_b32_e32 v1, 8, v3
	v_cmp_lt_i32_e32 vcc, v1, v6
	v_lshl_add_u64 v[8:9], v[4:5], 0, s[2:3]
	s_mov_b64 s[2:3], 0x1800
	v_cndmask_b32_e32 v1, v3, v1, vcc
	s_waitcnt vmcnt(18)
	v_lshlrev_b32_e32 v26, 2, v1
	v_xor_b32_e32 v1, 16, v3
	v_cmp_lt_i32_e32 vcc, v1, v6
	v_lshl_add_u64 v[6:7], v[4:5], 0, s[0:1]
	v_lshl_add_u64 v[10:11], v[4:5], 0, s[2:3]
	v_cndmask_b32_e32 v1, v3, v1, vcc
	v_lshlrev_b32_e32 v27, 2, v1
	v_ashrrev_i32_e32 v1, 31, v0
	v_lshlrev_b64 v[16:17], 13, v[0:1]
	v_or_b32_e32 v16, v16, v14
	v_lshlrev_b64 v[18:19], 7, v[0:1]
	v_lshl_add_u64 v[14:15], s[6:7], 0, v[16:17]
	v_lshl_or_b32 v18, v20, 2, v18
	s_mov_b64 s[2:3], 0x1c00
	v_lshl_add_u64 v[14:15], v[14:15], 0, s[0:1]
	v_ashrrev_i32_e32 v3, 31, v2
	v_lshl_add_u64 v[18:19], s[74:75], 0, v[18:19]
	s_mov_b64 s[0:1], 0x200000
	v_lshl_add_u64 v[12:13], v[4:5], 0, s[2:3]
	v_lshlrev_b64 v[16:17], 13, v[2:3]
	v_lshl_add_u64 v[18:19], v[18:19], 0, s[0:1]
	v_lshlrev_b64 v[20:21], 7, v[2:3]
	s_mov_b64 s[0:1], 0
	v_mov_b32_e32 v1, 0x358637bd
	global_load_dwordx4 v[44:47], v[4:5], off
	global_load_dwordx4 v[48:51], v[4:5], off offset:1024
	global_load_dwordx4 v[52:55], v[4:5], off offset:2048
	global_load_dwordx4 v[56:59], v[4:5], off offset:3072
	global_load_dwordx4 v[60:63], v[6:7], off
	global_load_dwordx4 v[64:67], v[8:9], off
	global_load_dwordx4 v[68:71], v[10:11], off
	global_load_dwordx4 v[72:75], v[12:13], off
	.p2alignl 6, 3212836864
